# speedup vs baseline: 1.0857x; 1.0086x over previous
; DI void gld(u32x4v& r, const void* p) { asm volatile("global_load_dwordx4 %0, %1, off" : "=v"(r) : "v"(p) : "memory"); }
; template <int DQK>
; DI void attn_phase(const bf16_t* Q, int ldq, const bf16_t* K1, int ldk1, const bf16_t* K2, int ldk2, const bf16_t* VT, int ldvt,
;                    bf16_t* O, int ldo, int nheads, int nq, int nkeys, bool causal, float scale, char* smem, int bid, int nb) {
;     ...
;   for (int it = bid; it < nitems; it += nb) {
;     const int qb = nqb - 1 - it / nheads, h = it % nheads;
;     const int q0 = qb * 128, qw = q0 + wid * 32;
;     constexpr int NKH = NKS;
;     bf16x8 qf[2][NKH];
; #pragma unroll
;     for (int mi = 0; mi < 2; ++mi)
; #pragma unroll
;       for (int ks = 0; ks < NKH; ++ks) qf[mi][ks] = *(const bf16x8*)(Q + (size_t)(qw + mi * 16 + fr) * ldq + h * DQK + ks * 32 + fq * 8);
;     f32x4 ot[2][8];
; #pragma unroll
;     for (int mi = 0; mi < 2; ++mi)
; #pragma unroll
;       for (int dj = 0; dj < 8; ++dj) ot[mi][dj] = (f32x4){0.f, 0.f, 0.f, 0.f};
;     float mrow[2] = {-1e30f, -1e30f}, lrow[2] = {0.f, 0.f};
;     const int ntiles = causal ? (q0 + 128) / 64 : nkeys / 64;
;     u32x4v kr[CPR / 4], vr[4];
;     {
;       int tl = tid; asm volatile("" : "+v"(tl));
; #pragma unroll
;       for (int j = 0; j < CPR / 4; ++j) {
;         const int c = tl + 256 * j, row = c / CPR, ch = c % CPR;
;         gld(kr[j], ch < 16 ? K1 + (size_t)row * ldk1 + h * 128 + ch * 8 : K2 + (size_t)row * ldk2 + (ch - 16) * 8);
;       }
; #pragma unroll
;       for (int j = 0; j < 4; ++j) { const int c = tl + 256 * j, d = c >> 3, ch = c & 7; gld(vr[j], VT + (size_t)(h * 128 + d) * ldvt + ch * 8); }
;     }
.Lattn_qb_keep:
	s_and_b32 s0, s0, -8
	s_sub_i32 s4, s2, s0
	s_lshl_b32 s0, s3, 7
	v_subrev_u32_e32 v234, s0, v229
	s_mul_i32 s0, s4, 0xc0
	v_or_b32_e32 v235, v234, v228
	s_ashr_i32 s1, s0, 31
	v_lshl_add_u64 v[0:1], s[0:1], 1, v[176:177]
	s_movk_i32 s5, 0xc00
	v_or_b32_e32 v236, 16, v235
	v_mad_i64_i32 v[2:3], s[0:1], v235, s5, v[0:1]
	v_mad_i64_i32 v[0:1], s[0:1], v236, s5, v[0:1]
	global_load_dwordx4 v[4:7], v[2:3], off
	global_load_dwordx4 v[8:11], v[2:3], off offset:64
	global_load_dwordx4 v[12:15], v[2:3], off offset:128
	global_load_dwordx4 v[16:19], v[2:3], off offset:192
	global_load_dwordx4 v[20:23], v[2:3], off offset:256
	global_load_dwordx4 v[24:27], v[2:3], off offset:320
	global_load_dwordx4 v[28:31], v[0:1], off
	global_load_dwordx4 v[32:35], v[0:1], off offset:64
	global_load_dwordx4 v[36:39], v[0:1], off offset:128
	global_load_dwordx4 v[40:43], v[0:1], off offset:192
	global_load_dwordx4 v[44:47], v[0:1], off offset:256
	global_load_dwordx4 v[48:51], v[0:1], off offset:320
	s_lshl_b32 s8, s4, 7
	s_ashr_i32 s9, s8, 31
	s_lshl_b64 s[6:7], s[8:9], 1
	v_readlane_b32 s0, v248, 63
	v_mov_b32_e32 v72, v226
	s_add_u32 s10, s0, s6
	v_readlane_b32 s1, v249, 0
	v_add_u32_e32 v76, 0x100, v72
	v_add_u32_e32 v80, 0x200, v72
	s_addc_u32 s11, s1, s7
	v_add_u32_e32 v84, 0x300, v72
	v_lshrrev_b32_e32 v64, 4, v72
	v_and_b32_e32 v65, 15, v72
	v_lshlrev_b32_e32 v65, 4, v65
	v_lshl_or_b32 v64, v64, 11, v65
	v_lshrrev_b32_e32 v69, 3, v72
	v_and_b32_e32 v70, 7, v72
	v_mul_u32_u24_e32 v69, 0x4200, v69
	v_lshl_add_u32 v69, v70, 4, v69
	s_mov_b32 s4, s10
	s_mov_b32 s5, s11
	global_load_dwordx4 v[0:3], v64, s[4:5]
	s_add_u32 s4, s4, 0x8000
	s_addc_u32 s5, s5, 0
	global_load_dwordx4 v[52:55], v64, s[4:5]
	s_add_u32 s4, s4, 0x8000
	s_addc_u32 s5, s5, 0
	global_load_dwordx4 v[56:59], v64, s[4:5]
	s_add_u32 s4, s4, 0x8000
	s_addc_u32 s5, s5, 0
	global_load_dwordx4 v[60:63], v64, s[4:5]
	v_readlane_b32 s0, v249, 1
	v_readlane_b32 s1, v249, 2
	s_add_u32 s4, s0, 0
	s_addc_u32 s5, s1, 0
	global_load_dwordx4 v[64:67], v69, s[4:5]
	s_add_u32 s4, s4, 0x84000
	s_addc_u32 s5, s5, 0
	global_load_dwordx4 v[68:71], v69, s[4:5]
	v_lshlrev_b32_e32 v73, 4, v72
	v_ashrrev_i32_e32 v72, 3, v72
	v_readlane_b32 s4, v249, 3
	v_add_u32_e32 v72, s8, v72
	v_ashrrev_i32_e32 v76, 3, v76
	v_and_b32_e32 v184, 0x70, v73
	v_readlane_b32 s5, v249, 4
	v_ashrrev_i32_e32 v73, 31, v72
	v_add_u32_e32 v76, s8, v76
	v_ashrrev_i32_e32 v80, 3, v80
	v_lshl_add_u64 v[86:87], s[4:5], 0, v[184:185]
	v_lshlrev_b64 v[72:73], 15, v[72:73]
	v_ashrrev_i32_e32 v77, 31, v76
	v_add_u32_e32 v80, s8, v80
	v_ashrrev_i32_e32 v84, 3, v84
	v_lshl_add_u64 v[72:73], v[86:87], 0, v[72:73]
	v_lshlrev_b64 v[76:77], 15, v[76:77]
	v_ashrrev_i32_e32 v81, 31, v80
	v_add_u32_e32 v84, s8, v84
	global_load_dwordx4 v[72:75], v[72:73], off
	v_lshl_add_u64 v[76:77], v[86:87], 0, v[76:77]
	v_lshlrev_b64 v[80:81], 15, v[80:81]
	v_ashrrev_i32_e32 v85, 31, v84
	global_load_dwordx4 v[76:79], v[76:77], off
	v_lshl_add_u64 v[80:81], v[86:87], 0, v[80:81]
	v_lshlrev_b64 v[84:85], 15, v[84:85]
	s_sub_i32 s0, 0, s3
	global_load_dwordx4 v[80:83], v[80:81], off
	v_lshl_add_u64 v[84:85], v[86:87], 0, v[84:85]
	s_lshl_b32 s0, s0, 7
	global_load_dwordx4 v[84:87], v[84:85], off
	s_addk_i32 s0, 0x4000
	s_cmp_eq_u32 s0, 0
	s_cbranch_scc1 .LBB0_1511
	v_mov_b32_e32 v184, v185
	v_mov_b32_e32 v100, 0
	s_lshr_b32 s3, s0, 6
	v_or_b32_e32 v237, 31, v234
	s_mov_b32 s14, 0
	v_mov_b32_e32 v180, 0xf149f2ca
	s_mov_b32 s9, 63
	v_mov_b32_e32 v152, 0xf149f2ca
	v_mov_b64_e32 v[178:179], v[184:185]
	v_mov_b32_e32 v101, v100
	v_mov_b32_e32 v102, v100
	v_mov_b32_e32 v103, v100
	v_mov_b32_e32 v108, v100
	v_mov_b32_e32 v109, v100
	v_mov_b32_e32 v110, v100
	v_mov_b32_e32 v111, v100
	v_mov_b32_e32 v112, v100
	v_mov_b32_e32 v113, v100
	v_mov_b32_e32 v114, v100
	v_mov_b32_e32 v115, v100
	v_mov_b32_e32 v116, v100
	v_mov_b32_e32 v117, v100
	v_mov_b32_e32 v118, v100
	v_mov_b32_e32 v119, v100
	v_mov_b32_e32 v132, v100
	v_mov_b32_e32 v133, v100
	v_mov_b32_e32 v134, v100
	v_mov_b32_e32 v135, v100
	v_mov_b32_e32 v120, v100
	v_mov_b32_e32 v121, v100
	v_mov_b32_e32 v122, v100
	v_mov_b32_e32 v123, v100
	v_mov_b32_e32 v124, v100
	v_mov_b32_e32 v125, v100
	v_mov_b32_e32 v126, v100
	v_mov_b32_e32 v127, v100
	v_mov_b32_e32 v128, v100
	v_mov_b32_e32 v129, v100
	v_mov_b32_e32 v130, v100
	v_mov_b32_e32 v131, v100
	v_mov_b32_e32 v136, v100
	v_mov_b32_e32 v137, v100
	v_mov_b32_e32 v138, v100
	v_mov_b32_e32 v139, v100
	v_mov_b32_e32 v140, v100
	v_mov_b32_e32 v141, v100
	v_mov_b32_e32 v142, v100
	v_mov_b32_e32 v143, v100
	v_mov_b32_e32 v144, v100
	v_mov_b32_e32 v145, v100
	v_mov_b32_e32 v146, v100
	v_mov_b32_e32 v147, v100
	v_mov_b32_e32 v148, v100
	v_mov_b32_e32 v149, v100
	v_mov_b32_e32 v150, v100
	v_mov_b32_e32 v151, v100
	v_mov_b32_e32 v96, v100
	v_mov_b32_e32 v97, v100
	v_mov_b32_e32 v98, v100
	v_mov_b32_e32 v99, v100
	v_mov_b32_e32 v88, v100
	v_mov_b32_e32 v89, v100
	v_mov_b32_e32 v90, v100
	v_mov_b32_e32 v91, v100
	v_mov_b32_e32 v92, v100
	v_mov_b32_e32 v93, v100
	v_mov_b32_e32 v94, v100
	v_mov_b32_e32 v95, v100
	v_mov_b32_e32 v104, v100
	v_mov_b32_e32 v105, v100
	v_mov_b32_e32 v106, v100
	v_mov_b32_e32 v107, v100
	s_branch .LBB0_1540

; template <int DQK>
; DI void attn_phase(const bf16_t* Q, int ldq, const bf16_t* K1, int ldk1, const bf16_t* K2, int ldk2, const bf16_t* VT, int ldvt,
;                    bf16_t* O, int ldo, int nheads, int nq, int nkeys, bool causal, float scale, char* smem, int bid, int nb) {
;     ...
;     for (int kt = 0; kt < ntiles; ++kt) {
;       const int s0 = kt * 64;
;       int tl = tid; asm volatile("" : "+v"(tl));
;       __syncthreads();
;       if (CPR / 4 == 6) asm volatile("s_waitcnt vmcnt(0)" : "+v"(kr[0]), "+v"(kr[1]), "+v"(kr[2]), "+v"(kr[3]), "+v"(kr[CPR / 4 - 2]), "+v"(kr[CPR / 4 - 1]), "+v"(vr[0]), "+v"(vr[1]), "+v"(vr[2]), "+v"(vr[3]) :: "memory");
;       else asm volatile("s_waitcnt vmcnt(0)" : "+v"(kr[0]), "+v"(kr[1]), "+v"(kr[2]), "+v"(kr[3]), "+v"(vr[0]), "+v"(vr[1]), "+v"(vr[2]), "+v"(vr[3]) :: "memory");
; #pragma unroll
;       for (int j = 0; j < CPR / 4; ++j) {
;         const int c = tl + 256 * j, row = c / CPR, ch = c % CPR;
;         *(u32x4v*)(Ks + row * LK * 2 + (((ch & ~7) | ((ch ^ (row >> 1)) & 7)) * 16)) = kr[j];
;       }
; #pragma unroll
;       for (int j = 0; j < 4; ++j) { const int c = tl + 256 * j, d = c >> 3, ch = c & 7; *(u32x4v*)(Vs + (d * LDT + ch * 8) * 2) = vr[j]; }
;       {
;         const int s1 = (kt + 1 < ntiles ? kt + 1 : kt) * 64;
; #pragma unroll
;         for (int j = 0; j < CPR / 4; ++j) {
;           const int c = tl + 256 * j, row = c / CPR, ch = c % CPR;
;           gld(kr[j], ch < 16 ? K1 + (size_t)(s1 + row) * ldk1 + h * 128 + ch * 8 : K2 + (size_t)(s1 + row) * ldk2 + (ch - 16) * 8);
;         }
; #pragma unroll
;         for (int j = 0; j < 4; ++j) { const int c = tl + 256 * j, d = c >> 3, ch = c & 7; gld(vr[j], VT + (size_t)(h * 128 + d) * ldvt + s1 + ch * 8); }
;       }
;       __syncthreads();
;       if (causal && s0 > qw + 31) continue;
;       f32x4 st[2][4];
; #pragma unroll
;       for (int mi = 0; mi < 2; ++mi)
; #pragma unroll
;         for (int nj = 0; nj < 4; ++nj) st[mi][nj] = (f32x4){0.f, 0.f, 0.f, 0.f};
;       asm volatile("" ::: "memory");
; #pragma unroll
;       for (int ks = 0; ks < NKS; ++ks) {
;         bf16x8 kf[4];
; #pragma unroll
;         for (int nj = 0; nj < 4; ++nj) kf[nj] = *(const bf16x8*)(Ks + (nj * 16 + fr) * LK * 2 + ((((ks * 4) & ~7) | (((ks * 4 + fq) ^ (fr >> 1)) & 7)) * 16));
;         bf16x8 qq[2];
; #pragma unroll
;         for (int mi = 0; mi < 2; ++mi) {
.LBB0_1540:
	v_mov_b32_e32 v153, v226
	v_lshrrev_b32_e32 v154, 4, v153
	v_and_b32_e32 v156, 15, v153
	v_lshrrev_b32_e32 v155, 1, v154
	v_xor_b32_e32 v155, v155, v156
	v_and_b32_e32 v155, 7, v155
	v_and_or_b32 v155, v156, 8, v155
	v_mul_u32_u24_e32 v154, 0x180, v154
	v_lshl_add_u32 v155, v155, 4, v154
	v_lshrrev_b32_e32 v157, 3, v153
	v_and_b32_e32 v158, 7, v153
	v_lshrrev_b32_e32 v159, 1, v157
	v_xor_b32_e32 v159, v159, v158
	v_and_b32_e32 v159, 7, v159
	v_lshlrev_b32_e32 v159, 4, v159
	v_mul_u32_u24_e32 v157, 0x180, v157
	v_add_u32_e32 v159, 0x100, v159
	v_add_u32_e32 v159, v157, v159
	s_waitcnt vmcnt(63) expcnt(7) lgkmcnt(15)
	s_barrier
	s_waitcnt vmcnt(0)
	ds_write_b128 v155, v[0:3]
	ds_write_b128 v155, v[52:55] offset:6144
	ds_write_b128 v155, v[56:59] offset:12288
	ds_write_b128 v155, v[60:63] offset:18432
	ds_write_b128 v159, v[64:67]
	ds_write_b128 v159, v[68:71] offset:12288
	v_add_u32_e32 v0, 0x100, v153
	v_add_u32_e32 v1, 0x200, v153
	v_add_u32_e32 v2, 0x300, v153
	v_lshrrev_b32_e32 v156, 3, v153
	v_and_b32_e32 v157, 7, v153
	v_mul_u32_u24_e32 v3, 0x90, v156
	v_lshl_add_u32 v3, v157, 4, v3
	s_mov_b32 s0, s14
	s_add_i32 s14, s14, 1
	ds_write_b128 v3, v[72:75] offset:24576
	ds_write_b128 v3, v[76:79] offset:29184
	s_cmp_lt_u32 s14, s3
	s_cselect_b32 s0, s14, s0
	v_readlane_b32 s5, v247, 48
	ds_write_b128 v3, v[80:83] offset:33792
	s_mov_b32 s1, s5
	s_lshl_b32 s0, s0, 6
	v_writelane_b32 v247, s0, 47
	ds_write_b128 v3, v[84:87] offset:38400
	v_writelane_b32 v247, s1, 48
	v_mov_b32_e32 v158, v226
	v_lshrrev_b32_e32 v159, 4, v158
	v_and_b32_e32 v160, 15, v158
	v_lshlrev_b32_e32 v160, 4, v160
	v_lshl_or_b32 v159, v159, 11, v160
	v_lshrrev_b32_e32 v161, 3, v158
	v_and_b32_e32 v162, 7, v158
	v_mul_u32_u24_e32 v161, 0x4200, v161
	v_lshl_add_u32 v161, v162, 4, v161
	s_lshl_b32 s4, s0, 11
	s_add_u32 s4, s10, s4
	s_addc_u32 s5, s11, 0
	global_load_dwordx4 v[0:3], v159, s[4:5]
	s_add_u32 s4, s4, 0x8000
	s_addc_u32 s5, s5, 0
	global_load_dwordx4 v[52:55], v159, s[4:5]
	s_add_u32 s4, s4, 0x8000
	s_addc_u32 s5, s5, 0
	global_load_dwordx4 v[56:59], v159, s[4:5]
	s_add_u32 s4, s4, 0x8000
	s_addc_u32 s5, s5, 0
	global_load_dwordx4 v[60:63], v159, s[4:5]
	v_readlane_b32 s4, v249, 1
	v_readlane_b32 s5, v249, 2
	s_mul_i32 s1, s0, 0x4200
	s_add_u32 s4, s4, s1
	s_addc_u32 s5, s5, 0
	global_load_dwordx4 v[64:67], v161, s[4:5]
	s_add_u32 s4, s4, 0x84000
	s_addc_u32 s5, s5, 0
	global_load_dwordx4 v[68:71], v161, s[4:5]
	v_readlane_b32 s4, v249, 3
	v_readlane_b32 s5, v249, 4
	s_lshl_b32 s1, s0, 1
	s_add_u32 s4, s4, s1
	s_addc_u32 s5, s5, 0
	s_lshl_b32 s1, s8, 15
	s_add_u32 s4, s4, s1
	s_addc_u32 s5, s5, 0
	v_lshlrev_b32_e32 v163, 4, v157
	v_lshl_or_b32 v163, v156, 15, v163
	global_load_dwordx4 v[72:75], v163, s[4:5]
	s_add_u32 s4, s4, 0x100000
	s_addc_u32 s5, s5, 0
	global_load_dwordx4 v[76:79], v163, s[4:5]
	s_add_u32 s4, s4, 0x100000
	s_addc_u32 s5, s5, 0
	global_load_dwordx4 v[80:83], v163, s[4:5]
	s_add_u32 s4, s4, 0x100000
	s_addc_u32 s5, s5, 0
	global_load_dwordx4 v[84:87], v163, s[4:5]
	s_sub_i32 s0, s9, 63
	v_cmp_le_i32_e32 vcc, s0, v237
	s_waitcnt lgkmcnt(0)
	s_barrier
	s_and_saveexec_b64 s[12:13], vcc
	s_cbranch_execz .LBB0_1539
	ds_read_b128 v[154:157], v231
	ds_read_b128 v[158:161], v231 offset:6144
	ds_read_b128 v[162:165], v231 offset:12288
	ds_read_b128 v[166:169], v231 offset:18432
	ds_read_b128 v[198:201], v232
	ds_read_b128 v[202:205], v232 offset:6144
	ds_read_b128 v[206:209], v232 offset:12288
	ds_read_b128 v[210:213], v232 offset:18432
	s_waitcnt lgkmcnt(7)
	v_mfma_f32_16x16x32_bf16 v[170:173], v[154:157], v[4:7], 0
	v_add_u32_e32 v153, s9, v230
	v_subrev_u32_e32 v182, 63, v153
	v_cmp_gt_i32_e32 vcc, s9, v234
	s_waitcnt lgkmcnt(6)
	v_mfma_f32_16x16x32_bf16 v[186:189], v[158:161], v[4:7], 0
	v_cmp_ge_i32_e64 s[4:5], v182, v235
	s_and_b64 s[4:5], vcc, s[4:5]
	v_cmp_gt_i32_e64 s[0:1], v182, v235
	s_waitcnt lgkmcnt(5)
	v_mfma_f32_16x16x32_bf16 v[190:193], v[162:165], v[4:7], 0
	s_and_b64 s[0:1], vcc, s[0:1]
	s_mov_b32 s17, 0xf149f2ca
	s_movk_i32 s16, 0x7fff
	s_waitcnt lgkmcnt(4)
	v_mfma_f32_16x16x32_bf16 v[194:197], v[166:169], v[4:7], 0
	s_mov_b32 s15, 0xffff0000
	v_add_u32_e32 v244, 0x6800, v233
	v_add_u32_e32 v245, 0x7000, v233
	s_nop 0
	v_mfma_f32_16x16x32_bf16 v[154:157], v[154:157], v[28:31], 0
	v_add_u32_e32 v221, 0x7800, v233
	v_add_u32_e32 v215, 0x8000, v233
	v_add_u32_e32 v216, 0x8800, v233
	v_mfma_f32_16x16x32_bf16 v[158:161], v[158:161], v[28:31], 0
	v_add_u32_e32 v224, 0x9000, v233
	v_add_u32_e32 v225, 0x9800, v233
	v_mfma_f32_16x16x32_bf16 v[162:165], v[162:165], v[28:31], 0
	v_mfma_f32_16x16x32_bf16 v[166:169], v[166:169], v[28:31], 0
	s_waitcnt lgkmcnt(3)
	v_mfma_f32_16x16x32_bf16 v[170:173], v[198:201], v[8:11], v[170:173]
	s_waitcnt lgkmcnt(2)
	v_mfma_f32_16x16x32_bf16 v[186:189], v[202:205], v[8:11], v[186:189]
	s_waitcnt lgkmcnt(1)
	v_mfma_f32_16x16x32_bf16 v[190:193], v[206:209], v[8:11], v[190:193]
	s_waitcnt lgkmcnt(0)
	v_mfma_f32_16x16x32_bf16 v[194:197], v[210:213], v[8:11], v[194:197]
	s_nop 0
	v_mfma_f32_16x16x32_bf16 v[154:157], v[198:201], v[32:35], v[154:157]
	v_mfma_f32_16x16x32_bf16 v[158:161], v[202:205], v[32:35], v[158:161]
	v_mfma_f32_16x16x32_bf16 v[162:165], v[206:209], v[32:35], v[162:165]
	v_mfma_f32_16x16x32_bf16 v[166:169], v[210:213], v[32:35], v[166:169]
	ds_read_b128 v[198:201], v231 offset:128
	ds_read_b128 v[202:205], v231 offset:6272
	ds_read_b128 v[206:209], v231 offset:12416
	ds_read_b128 v[210:213], v231 offset:18560
	s_waitcnt lgkmcnt(3)
	v_mfma_f32_16x16x32_bf16 v[170:173], v[198:201], v[12:15], v[170:173]
	s_waitcnt lgkmcnt(2)
	v_mfma_f32_16x16x32_bf16 v[186:189], v[202:205], v[12:15], v[186:189]
	s_waitcnt lgkmcnt(1)
; #define MFMA16(a, b, c) __builtin_amdgcn_mfma_f32_16x16x32_bf16((a), (b), (c), 0, 0, 0)
; template <int DQK>
; DI void attn_phase(const bf16_t* Q, int ldq, const bf16_t* K1, int ldk1, const bf16_t* K2, int ldk2, const bf16_t* VT, int ldvt,
;                    bf16_t* O, int ldo, int nheads, int nq, int nkeys, bool causal, float scale, char* smem, int bid, int nb) {
;     ...
;       for (int ks = 0; ks < NKS; ++ks) {
;         bf16x8 kf[4];
; #pragma unroll
;         for (int nj = 0; nj < 4; ++nj) kf[nj] = *(const bf16x8*)(Ks + (nj * 16 + fr) * LK * 2 + ((((ks * 4) & ~7) | (((ks * 4 + fq) ^ (fr >> 1)) & 7)) * 16));
;         bf16x8 qq[2];
; #pragma unroll
;         for (int mi = 0; mi < 2; ++mi) {
;           if (ks < NKH) qq[mi] = qf[mi][ks < NKH ? ks : 0];
;           else qq[mi] = *(const bf16x8*)(Q + (size_t)(qw + mi * 16 + fr) * ldq + h * DQK + ks * 32 + fq * 8);
;         }
; #pragma unroll
;         for (int mi = 0; mi < 2; ++mi)
; #pragma unroll
;           for (int nj = 0; nj < 4; ++nj) st[mi][nj] = MFMA16(kf[nj], qq[mi], st[mi][nj]);
;       }
;       const bool diag = causal && (s0 + 63 > qw);
;       bf16x8 pf[2][2];
; #pragma unroll
;       for (int mi = 0; mi < 2; ++mi) {
;         const int qi = qw + mi * 16 + fr;
;         float mx = -1e30f;
; #pragma unroll
;         for (int nj = 0; nj < 4; ++nj)
; #pragma unroll
;           for (int r = 0; r < 4; ++r) {
;             float v = st[mi][nj][r] * sc2;
;             if (diag && (s0 + nj * 16 + fq * 4 + r > qi)) v = -1e30f;
;             st[mi][nj][r] = v; mx = fmaxf(mx, v);
;           }
;         mx = rows4_max(mx);
	v_mfma_f32_16x16x32_bf16 v[190:193], v[206:209], v[12:15], v[190:193]
	s_waitcnt lgkmcnt(0)
	v_mfma_f32_16x16x32_bf16 v[194:197], v[210:213], v[12:15], v[194:197]
	s_nop 0
	v_mfma_f32_16x16x32_bf16 v[154:157], v[198:201], v[36:39], v[154:157]
	v_mfma_f32_16x16x32_bf16 v[158:161], v[202:205], v[36:39], v[158:161]
	v_mfma_f32_16x16x32_bf16 v[162:165], v[206:209], v[36:39], v[162:165]
	v_mfma_f32_16x16x32_bf16 v[166:169], v[210:213], v[36:39], v[166:169]
	ds_read_b128 v[198:201], v232 offset:128
	ds_read_b128 v[202:205], v232 offset:6272
	ds_read_b128 v[206:209], v232 offset:12416
	ds_read_b128 v[210:213], v232 offset:18560
	s_waitcnt lgkmcnt(3)
	v_mfma_f32_16x16x32_bf16 v[170:173], v[198:201], v[16:19], v[170:173]
	s_waitcnt lgkmcnt(2)
	v_mfma_f32_16x16x32_bf16 v[186:189], v[202:205], v[16:19], v[186:189]
	s_waitcnt lgkmcnt(1)
	v_mfma_f32_16x16x32_bf16 v[190:193], v[206:209], v[16:19], v[190:193]
	s_waitcnt lgkmcnt(0)
	v_mfma_f32_16x16x32_bf16 v[194:197], v[210:213], v[16:19], v[194:197]
	s_nop 0
	v_mfma_f32_16x16x32_bf16 v[154:157], v[198:201], v[40:43], v[154:157]
	v_mfma_f32_16x16x32_bf16 v[158:161], v[202:205], v[40:43], v[158:161]
	v_mfma_f32_16x16x32_bf16 v[162:165], v[206:209], v[40:43], v[162:165]
	v_mfma_f32_16x16x32_bf16 v[166:169], v[210:213], v[40:43], v[166:169]
	ds_read_b128 v[198:201], v231 offset:256
	ds_read_b128 v[202:205], v231 offset:6400
	ds_read_b128 v[206:209], v231 offset:12544
	ds_read_b128 v[210:213], v231 offset:18688
	s_waitcnt lgkmcnt(3)
	v_mfma_f32_16x16x32_bf16 v[170:173], v[198:201], v[20:23], v[170:173]
	s_waitcnt lgkmcnt(2)
	v_mfma_f32_16x16x32_bf16 v[186:189], v[202:205], v[20:23], v[186:189]
	s_waitcnt lgkmcnt(1)
	v_mfma_f32_16x16x32_bf16 v[190:193], v[206:209], v[20:23], v[190:193]
	s_waitcnt lgkmcnt(0)
	v_mfma_f32_16x16x32_bf16 v[194:197], v[210:213], v[20:23], v[194:197]
	s_nop 0
	v_mfma_f32_16x16x32_bf16 v[154:157], v[198:201], v[44:47], v[154:157]
	v_mfma_f32_16x16x32_bf16 v[158:161], v[202:205], v[44:47], v[158:161]
	v_mfma_f32_16x16x32_bf16 v[162:165], v[206:209], v[44:47], v[162:165]
	v_mfma_f32_16x16x32_bf16 v[198:201], v[210:213], v[44:47], v[166:169]
	s_nop 2
	ds_read_b128 v[166:169], v232 offset:256
	ds_read_b128 v[202:205], v232 offset:6400
	ds_read_b128 v[206:209], v232 offset:12544
	ds_read_b128 v[210:213], v232 offset:18688
	s_waitcnt lgkmcnt(3)
	v_mfma_f32_16x16x32_bf16 v[238:241], v[166:169], v[24:27], v[170:173]
	s_nop 0
	v_mfma_f32_16x16x32_bf16 v[172:175], v[166:169], v[48:51], v[154:157]
	s_waitcnt lgkmcnt(2)
	v_mfma_f32_16x16x32_bf16 v[168:171], v[202:205], v[48:51], v[158:161]
	s_nop 3
	v_mul_f32_e32 v155, 0x3dd53b94, v239
	v_cndmask_b32_e64 v155, v155, v223, s[4:5]
	v_mul_f32_e32 v157, 0x3dd53b94, v240
	s_waitcnt lgkmcnt(1)
	v_mfma_f32_16x16x32_bf16 v[164:167], v[206:209], v[48:51], v[162:165]
	v_mul_f32_e32 v158, 0x3dd53b94, v241
	v_subrev_u32_e32 v159, 47, v153
	v_mul_f32_e32 v154, 0x3dd53b94, v238
	s_waitcnt lgkmcnt(0)
	v_mfma_f32_16x16x32_bf16 v[160:163], v[210:213], v[48:51], v[198:201]
	v_cndmask_b32_e64 v154, v154, v223, s[0:1]
	v_max3_f32 v156, v154, s17, v155
	v_add_u32_e32 v240, -12, v153
	v_subrev_u32_e32 v198, 61, v153
	v_cmp_gt_i32_e64 s[4:5], v198, v235
	v_mfma_f32_16x16x32_bf16 v[186:189], v[202:205], v[24:27], v[186:189]
	s_and_b64 s[4:5], vcc, s[4:5]
	v_subrev_u32_e32 v200, 60, v153
	v_cndmask_b32_e64 v157, v157, v223, s[4:5]
	v_cmp_gt_i32_e64 s[4:5], v200, v235
	s_and_b64 s[4:5], vcc, s[4:5]
	s_nop 2
	v_mul_f32_e32 v181, 0x3dd53b94, v186
	v_cndmask_b32_e64 v158, v158, v223, s[4:5]
	v_cmp_gt_i32_e64 s[4:5], v159, v235
	s_and_b64 s[4:5], vcc, s[4:5]
	v_subrev_u32_e32 v186, 46, v153
	v_cndmask_b32_e64 v159, v181, v223, s[4:5]
	v_cmp_gt_i32_e64 s[4:5], v186, v235
	v_mul_f32_e32 v181, 0x3dd53b94, v187
	s_and_b64 s[4:5], vcc, s[4:5]
	v_cndmask_b32_e64 v183, v181, v223, s[4:5]
	v_mul_f32_e32 v181, 0x3dd53b94, v188
	v_subrev_u32_e32 v188, 45, v153
	v_cmp_gt_i32_e64 s[4:5], v188, v235
	v_mfma_f32_16x16x32_bf16 v[190:193], v[206:209], v[24:27], v[190:193]
	s_and_b64 s[4:5], vcc, s[4:5]
	v_subrev_u32_e32 v202, 44, v153
	v_cndmask_b32_e64 v184, v181, v223, s[4:5]
	v_cmp_gt_i32_e64 s[4:5], v202, v235
	v_mul_f32_e32 v181, 0x3dd53b94, v189
	s_and_b64 s[4:5], vcc, s[4:5]
	v_subrev_u32_e32 v204, 31, v153
	v_cndmask_b32_e64 v201, v181, v223, s[4:5]
	v_cmp_gt_i32_e64 s[4:5], v204, v235
	v_mul_f32_e32 v181, 0x3dd53b94, v190
	s_and_b64 s[4:5], vcc, s[4:5]
	v_subrev_u32_e32 v206, 30, v153
	v_cndmask_b32_e64 v190, v181, v223, s[4:5]
	v_cmp_gt_i32_e64 s[4:5], v206, v235
	v_mul_f32_e32 v181, 0x3dd53b94, v191
	s_and_b64 s[4:5], vcc, s[4:5]
	v_cndmask_b32_e64 v191, v181, v223, s[4:5]
	v_mul_f32_e32 v181, 0x3dd53b94, v192
	v_subrev_u32_e32 v192, 29, v153
	v_cmp_gt_i32_e64 s[4:5], v192, v235
	v_mfma_f32_16x16x32_bf16 v[194:197], v[210:213], v[24:27], v[194:197]
	s_and_b64 s[4:5], vcc, s[4:5]
	v_subrev_u32_e32 v208, 28, v153
	v_cndmask_b32_e64 v203, v181, v223, s[4:5]
	v_cmp_gt_i32_e64 s[4:5], v208, v235
	v_mul_f32_e32 v181, 0x3dd53b94, v193
	s_and_b64 s[4:5], vcc, s[4:5]
	v_add_u32_e32 v210, -15, v153
	v_cndmask_b32_e64 v209, v181, v223, s[4:5]
	v_cmp_gt_i32_e64 s[4:5], v210, v235
	v_mul_f32_e32 v181, 0x3dd53b94, v194
	s_and_b64 s[4:5], vcc, s[4:5]
	v_add_u32_e32 v212, -14, v153
	v_cndmask_b32_e64 v194, v181, v223, s[4:5]
	v_cmp_gt_i32_e64 s[4:5], v212, v235
	v_mul_f32_e32 v181, 0x3dd53b94, v195
	s_and_b64 s[4:5], vcc, s[4:5]
	v_max3_f32 v156, v156, v157, v158
	v_cndmask_b32_e64 v211, v181, v223, s[4:5]
	v_mul_f32_e32 v181, 0x3dd53b94, v196
	v_add_u32_e32 v196, -13, v153
	v_max3_f32 v156, v156, v159, v183
	v_cmp_gt_i32_e64 s[4:5], v196, v235
	v_max3_f32 v156, v156, v184, v201
; DI unsigned pack2(float a, float b) { return (unsigned)f2bf(a) | ((unsigned)f2bf(b) << 16); }
; template <int DQK>
; DI void attn_phase(const bf16_t* Q, int ldq, const bf16_t* K1, int ldk1, const bf16_t* K2, int ldk2, const bf16_t* VT, int ldvt,
;                    bf16_t* O, int ldo, int nheads, int nq, int nkeys, bool causal, float scale, char* smem, int bid, int nb) {
;     ...
; #pragma unroll
;       for (int mi = 0; mi < 2; ++mi) {
;         const int qi = qw + mi * 16 + fr;
;         float mx = -1e30f;
; #pragma unroll
;         for (int nj = 0; nj < 4; ++nj)
; #pragma unroll
;           for (int r = 0; r < 4; ++r) {
;             float v = st[mi][nj][r] * sc2;
;             if (diag && (s0 + nj * 16 + fq * 4 + r > qi)) v = -1e30f;
;             st[mi][nj][r] = v; mx = fmaxf(mx, v);
;           }
;         mx = rows4_max(mx);
;         const float mn = fmaxf(mrow[mi], mx), al = __builtin_amdgcn_exp2f(mrow[mi] - mn);
;         mrow[mi] = mn;
;         float ps = 0.f;
; #pragma unroll
;         for (int nj = 0; nj < 4; ++nj)
; #pragma unroll
;           for (int r = 0; r < 4; ++r) { const float pv = __builtin_amdgcn_exp2f(st[mi][nj][r] - mn); st[mi][nj][r] = pv; ps += pv; }
;         lrow[mi] = lrow[mi] * al + ps;
; #pragma unroll
;         for (int dj = 0; dj < 8; ++dj) ot[mi][dj] *= al;
; #pragma unroll
;         for (int s = 0; s < 2; ++s) {
;           uint4 w;
;           w.x = pack2(st[mi][2 * s][0], st[mi][2 * s][1]); w.y = pack2(st[mi][2 * s][2], st[mi][2 * s][3]);
;           w.z = pack2(st[mi][2 * s + 1][0], st[mi][2 * s + 1][1]); w.w = pack2(st[mi][2 * s + 1][2], st[mi][2 * s + 1][3]);
;           pf[mi][s] = __builtin_bit_cast(bf16x8, w);
;         }
;       }
	s_and_b64 s[4:5], vcc, s[4:5]
	v_max3_f32 v156, v156, v190, v191
	v_cndmask_b32_e64 v239, v181, v223, s[4:5]
	v_cmp_gt_i32_e64 s[4:5], v240, v235
	v_max3_f32 v156, v156, v203, v209
	v_mul_f32_e32 v181, 0x3dd53b94, v197
	s_and_b64 s[4:5], vcc, s[4:5]
	v_max3_f32 v156, v156, v194, v211
	v_cndmask_b32_e64 v153, v181, v223, s[4:5]
	v_max3_f32 v156, v156, v239, v153
	v_mov_b32_e32 v181, v156
	s_nop 1
	v_permlane32_swap_b32_e32 v156, v181
	v_max_f32_e32 v181, v181, v181
	v_max_f32_e32 v156, v156, v156
	v_max_f32_e32 v156, v156, v181
	v_mov_b32_e32 v181, v156
	s_nop 1
	v_permlane16_swap_b32_e32 v156, v181
	v_max3_f32 v238, v152, v156, v181
	v_sub_f32_e32 v154, v154, v238
	v_exp_f32_e32 v181, v154
	v_sub_f32_e32 v154, v155, v238
	v_exp_f32_e32 v189, v154
	v_sub_f32_e32 v154, v157, v238
	v_exp_f32_e32 v187, v154
	v_sub_f32_e32 v154, v158, v238
	v_exp_f32_e32 v199, v154
	v_sub_f32_e32 v154, v159, v238
	v_mul_f32_e32 v168, 0x3dd53b94, v168
	v_exp_f32_e32 v193, v154
	v_sub_f32_e32 v154, v183, v238
	v_cndmask_b32_e64 v168, v168, v223, s[0:1]
	v_cmp_gt_i32_e64 s[0:1], v186, v236
	v_exp_f32_e32 v207, v154
	v_sub_f32_e32 v154, v184, v238
	v_mul_f32_e32 v169, 0x3dd53b94, v169
	s_and_b64 s[0:1], vcc, s[0:1]
	v_exp_f32_e32 v205, v154
	v_sub_f32_e32 v154, v201, v238
	v_cndmask_b32_e64 v169, v169, v223, s[0:1]
	v_cmp_gt_i32_e64 s[0:1], v188, v236
	v_exp_f32_e32 v213, v154
	v_sub_f32_e32 v154, v190, v238
	v_mul_f32_e32 v170, 0x3dd53b94, v170
	s_and_b64 s[0:1], vcc, s[0:1]
	v_sub_f32_e32 v152, v152, v238
	v_exp_f32_e32 v183, v154
	v_sub_f32_e32 v154, v191, v238
	v_cndmask_b32_e64 v170, v170, v223, s[0:1]
	v_cmp_gt_i32_e64 s[0:1], v202, v236
	v_exp_f32_e32 v197, v154
	v_sub_f32_e32 v154, v203, v238
	v_exp_f32_e32 v184, v152
	v_mul_f32_e32 v171, 0x3dd53b94, v171
	s_and_b64 s[0:1], vcc, s[0:1]
	v_exp_f32_e32 v191, v154
	v_sub_f32_e32 v154, v209, v238
	v_cndmask_b32_e64 v171, v171, v223, s[0:1]
	v_cmp_gt_i32_e64 s[0:1], v204, v236
	v_exp_f32_e32 v203, v154
	v_sub_f32_e32 v154, v194, v238
	v_mul_f32_e32 v164, 0x3dd53b94, v164
	s_and_b64 s[0:1], vcc, s[0:1]
	v_exp_f32_e32 v195, v154
	v_sub_f32_e32 v154, v211, v238
	v_cmp_gt_i32_e64 s[4:5], v182, v236
	v_cndmask_b32_e64 v164, v164, v223, s[0:1]
	v_cmp_gt_i32_e64 s[0:1], v206, v236
	v_exp_f32_e32 v209, v154
	v_sub_f32_e32 v154, v239, v238
	v_sub_f32_e32 v153, v153, v238
	v_pk_mul_f32 v[158:159], v[150:151], v[184:185] op_sel_hi:[1,0]
	v_pk_mul_f32 v[150:151], v[142:143], v[184:185] op_sel_hi:[1,0]
	v_pk_mul_f32 v[142:143], v[130:131], v[184:185] op_sel_hi:[1,0]
	v_bfe_u32 v130, v199, 16, 1
	v_bfe_u32 v131, v189, 16, 1
	v_mul_f32_e32 v172, 0x3dd53b94, v172
	s_and_b64 s[4:5], vcc, s[4:5]
	v_mul_f32_e32 v165, 0x3dd53b94, v165
	s_and_b64 s[0:1], vcc, s[0:1]
	v_exp_f32_e32 v201, v154
	v_exp_f32_e32 v211, v153
	v_pk_mul_f32 v[154:155], v[146:147], v[184:185] op_sel_hi:[1,0]
	v_pk_mul_f32 v[152:153], v[144:145], v[184:185] op_sel_hi:[1,0]
	v_pk_mul_f32 v[146:147], v[138:139], v[184:185] op_sel_hi:[1,0]
	v_pk_mul_f32 v[144:145], v[136:137], v[184:185] op_sel_hi:[1,0]
	v_pk_mul_f32 v[138:139], v[126:127], v[184:185] op_sel_hi:[1,0]
	v_pk_mul_f32 v[136:137], v[124:125], v[184:185] op_sel_hi:[1,0]
	v_pk_mul_f32 v[126:127], v[122:123], v[184:185] op_sel_hi:[1,0]
	v_pk_mul_f32 v[124:125], v[120:121], v[184:185] op_sel_hi:[1,0]
	v_pk_mul_f32 v[122:123], v[134:135], v[184:185] op_sel_hi:[1,0]
	v_pk_mul_f32 v[120:121], v[132:133], v[184:185] op_sel_hi:[1,0]
	v_add3_u32 v132, v189, v131, s16
	v_add3_u32 v133, v199, v130, s16
	v_bfe_u32 v130, v181, 16, 1
	v_bfe_u32 v131, v187, 16, 1
	v_bfe_u32 v134, v193, 16, 1
	v_bfe_u32 v135, v205, 16, 1
	v_cndmask_b32_e64 v172, v172, v223, s[4:5]
	v_cmp_ge_i32_e64 s[4:5], v182, v236
	v_cndmask_b32_e64 v165, v165, v223, s[0:1]
	v_cmp_gt_i32_e64 s[0:1], v192, v236
	v_pk_mul_f32 v[156:157], v[148:149], v[184:185] op_sel_hi:[1,0]
	v_pk_mul_f32 v[148:149], v[140:141], v[184:185] op_sel_hi:[1,0]
	v_pk_mul_f32 v[140:141], v[128:129], v[184:185] op_sel_hi:[1,0]
	v_bfe_u32 v128, v213, 16, 1
	v_bfe_u32 v129, v207, 16, 1
	v_add3_u32 v135, v205, v135, s16
	v_add3_u32 v134, v193, v134, s16
	v_add3_u32 v131, v187, v131, s16
	v_add3_u32 v130, v181, v130, s16
	v_mul_f32_e32 v173, 0x3dd53b94, v173
	s_and_b64 s[4:5], vcc, s[4:5]
	v_mul_f32_e32 v166, 0x3dd53b94, v166
	s_and_b64 s[0:1], vcc, s[0:1]
	v_add3_u32 v129, v207, v129, s16
	v_add3_u32 v128, v213, v128, s16
	v_lshrrev_b32_e32 v190, 16, v130
	v_lshrrev_b32_e32 v194, 16, v131
	v_lshrrev_b32_e32 v130, 16, v134
	v_lshrrev_b32_e32 v131, 16, v135
	v_bfe_u32 v134, v203, 16, 1
	v_bfe_u32 v135, v197, 16, 1
	v_cndmask_b32_e64 v173, v173, v223, s[4:5]
	v_cmp_gt_i32_e64 s[4:5], v198, v236
	v_cndmask_b32_e64 v166, v166, v223, s[0:1]
	v_cmp_gt_i32_e64 s[0:1], v208, v236
	v_and_or_b32 v131, v128, s15, v131
	v_and_or_b32 v130, v129, s15, v130
	v_and_or_b32 v129, v133, s15, v194
	v_and_or_b32 v128, v132, s15, v190
	v_add3_u32 v190, v197, v135, s16
	v_add3_u32 v194, v203, v134, s16
	v_bfe_u32 v134, v183, 16, 1
	v_bfe_u32 v135, v191, 16, 1
	v_bfe_u32 v239, v195, 16, 1
	v_mul_f32_e32 v174, 0x3dd53b94, v174
	s_and_b64 s[4:5], vcc, s[4:5]
	v_mul_f32_e32 v167, 0x3dd53b94, v167
	s_and_b64 s[0:1], vcc, s[0:1]
	v_bfe_u32 v133, v209, 16, 1
	v_add3_u32 v239, v195, v239, s16
	v_add3_u32 v135, v191, v135, s16
	v_add3_u32 v134, v183, v134, s16
	v_cndmask_b32_e64 v174, v174, v223, s[4:5]
	v_cmp_gt_i32_e64 s[4:5], v200, v236
	v_cndmask_b32_e64 v167, v167, v223, s[0:1]
	v_cmp_gt_i32_e64 s[0:1], v210, v236
	v_add3_u32 v133, v209, v133, s16
	v_lshrrev_b32_e32 v242, 16, v134
	v_lshrrev_b32_e32 v243, 16, v135
	v_lshrrev_b32_e32 v134, 16, v239
	v_mul_f32_e32 v175, 0x3dd53b94, v175
; DI unsigned pack2(float a, float b) { return (unsigned)f2bf(a) | ((unsigned)f2bf(b) << 16); }
; template <int DQK>
; DI void attn_phase(const bf16_t* Q, int ldq, const bf16_t* K1, int ldk1, const bf16_t* K2, int ldk2, const bf16_t* VT, int ldvt,
;                    bf16_t* O, int ldo, int nheads, int nq, int nkeys, bool causal, float scale, char* smem, int bid, int nb) {
;     ...
;             float v = st[mi][nj][r] * sc2;
;             if (diag && (s0 + nj * 16 + fq * 4 + r > qi)) v = -1e30f;
;             st[mi][nj][r] = v; mx = fmaxf(mx, v);
;           }
;         mx = rows4_max(mx);
;         const float mn = fmaxf(mrow[mi], mx), al = __builtin_amdgcn_exp2f(mrow[mi] - mn);
;         mrow[mi] = mn;
;         float ps = 0.f;
; #pragma unroll
;         for (int nj = 0; nj < 4; ++nj)
; #pragma unroll
;           for (int r = 0; r < 4; ++r) { const float pv = __builtin_amdgcn_exp2f(st[mi][nj][r] - mn); st[mi][nj][r] = pv; ps += pv; }
;         lrow[mi] = lrow[mi] * al + ps;
; #pragma unroll
;         for (int dj = 0; dj < 8; ++dj) ot[mi][dj] *= al;
; #pragma unroll
;         for (int s = 0; s < 2; ++s) {
;           uint4 w;
;           w.x = pack2(st[mi][2 * s][0], st[mi][2 * s][1]); w.y = pack2(st[mi][2 * s][2], st[mi][2 * s][3]);
;           w.z = pack2(st[mi][2 * s + 1][0], st[mi][2 * s + 1][1]); w.w = pack2(st[mi][2 * s + 1][2], st[mi][2 * s + 1][3]);
;           pf[mi][s] = __builtin_bit_cast(bf16x8, w);
;         }
;       }
; #pragma unroll
;       for (int s = 0; s < 2; ++s)
; #pragma unroll
;         for (int dj = 0; dj < 8; ++dj) {
;           const char* vp = Vs + ((dj * 16 + fr) * LDT + 32 * s + fq * 4) * 2;
;           const s16x4 lo = *(const s16x4*)vp, hi = *(const s16x4*)(vp + 32);
	s_and_b64 s[4:5], vcc, s[4:5]
	v_mul_f32_e32 v160, 0x3dd53b94, v160
	s_and_b64 s[0:1], vcc, s[0:1]
	v_and_or_b32 v134, v133, s15, v134
	v_and_or_b32 v133, v194, s15, v243
	v_max3_f32 v182, v172, s17, v173
	v_cndmask_b32_e64 v175, v175, v223, s[4:5]
	v_cndmask_b32_e64 v194, v160, v223, s[0:1]
	v_cmp_gt_i32_e64 s[0:1], v212, v236
	v_max3_f32 v182, v182, v174, v175
	v_mul_f32_e32 v160, 0x3dd53b94, v161
	s_and_b64 s[0:1], vcc, s[0:1]
	v_max3_f32 v182, v182, v168, v169
	v_cndmask_b32_e64 v200, v160, v223, s[0:1]
	v_cmp_gt_i32_e64 s[0:1], v196, v236
	v_max3_f32 v182, v182, v170, v171
	v_mul_f32_e32 v161, 0x3dd53b94, v162
	s_and_b64 s[0:1], vcc, s[0:1]
	v_max3_f32 v182, v182, v164, v165
	v_cndmask_b32_e64 v162, v161, v223, s[0:1]
	v_cmp_gt_i32_e64 s[0:1], v240, v236
	v_max3_f32 v182, v182, v166, v167
	v_mul_f32_e32 v161, 0x3dd53b94, v163
	s_and_b64 vcc, vcc, s[0:1]
	v_max3_f32 v160, v182, v194, v200
	v_cndmask_b32_e32 v163, v161, v223, vcc
	v_max3_f32 v160, v160, v162, v163
	v_mov_b32_e32 v161, v160
	s_nop 1
	v_permlane32_swap_b32_e32 v160, v161
	v_max_f32_e32 v161, v161, v161
	v_max_f32_e32 v160, v160, v160
	v_max_f32_e32 v160, v160, v161
	v_mov_b32_e32 v161, v160
	s_nop 1
	v_permlane16_swap_b32_e32 v160, v161
	v_max3_f32 v239, v180, v160, v161
	v_sub_f32_e32 v160, v172, v239
	v_sub_f32_e32 v240, v180, v239
	v_exp_f32_e32 v180, v160
	v_sub_f32_e32 v160, v173, v239
	v_exp_f32_e32 v188, v160
	v_sub_f32_e32 v160, v174, v239
	v_exp_f32_e32 v186, v160
	v_sub_f32_e32 v160, v175, v239
	v_exp_f32_e32 v198, v160
	v_sub_f32_e32 v160, v168, v239
	v_exp_f32_e32 v192, v160
	v_sub_f32_e32 v160, v169, v239
	v_exp_f32_e32 v206, v160
	v_sub_f32_e32 v160, v170, v239
	v_exp_f32_e32 v204, v160
	v_sub_f32_e32 v160, v171, v239
	v_exp_f32_e32 v212, v160
	v_pk_add_f32 v[160:161], v[180:181], 0 op_sel_hi:[1,0]
	v_bfe_u32 v241, v201, 16, 1
	v_pk_add_f32 v[160:161], v[188:189], v[160:161]
	v_sub_f32_e32 v164, v164, v239
	v_pk_add_f32 v[160:161], v[186:187], v[160:161]
	v_bfe_u32 v132, v211, 16, 1
	v_pk_add_f32 v[160:161], v[198:199], v[160:161]
	v_add3_u32 v241, v201, v241, s16
	v_pk_add_f32 v[160:161], v[192:193], v[160:161]
	v_exp_f32_e32 v182, v164
	v_sub_f32_e32 v164, v165, v239
	v_add3_u32 v132, v211, v132, s16
	v_lshrrev_b32_e32 v135, 16, v241
	v_pk_add_f32 v[160:161], v[206:207], v[160:161]
	v_exp_f32_e32 v196, v164
	v_sub_f32_e32 v164, v166, v239
	v_and_or_b32 v135, v132, s15, v135
	v_and_or_b32 v132, v190, s15, v242
	v_pk_add_f32 v[160:161], v[204:205], v[160:161]
	v_exp_f32_e32 v190, v164
	v_sub_f32_e32 v164, v167, v239
	v_pk_add_f32 v[160:161], v[212:213], v[160:161]
	v_exp_f32_e32 v202, v164
	v_sub_f32_e32 v164, v194, v239
	v_exp_f32_e32 v194, v164
	v_sub_f32_e32 v164, v200, v239
	v_sub_f32_e32 v162, v162, v239
	v_pk_add_f32 v[160:161], v[182:183], v[160:161]
	v_exp_f32_e32 v208, v164
	v_exp_f32_e32 v200, v162
	v_sub_f32_e32 v162, v163, v239
	v_pk_add_f32 v[160:161], v[196:197], v[160:161]
	v_exp_f32_e32 v210, v162
	v_exp_f32_e32 v162, v240
	v_pk_add_f32 v[160:161], v[190:191], v[160:161]
	v_mov_b32_e32 v163, v184
	v_pk_add_f32 v[160:161], v[202:203], v[160:161]
	v_pk_mul_f32 v[170:171], v[118:119], v[162:163] op_sel_hi:[1,0]
	v_pk_add_f32 v[160:161], v[194:195], v[160:161]
	v_pk_mul_f32 v[168:169], v[116:117], v[162:163] op_sel_hi:[1,0]
	v_pk_add_f32 v[160:161], v[208:209], v[160:161]
	v_pk_mul_f32 v[118:119], v[110:111], v[162:163] op_sel_hi:[1,0]
	v_pk_add_f32 v[160:161], v[200:201], v[160:161]
	v_pk_mul_f32 v[116:117], v[108:109], v[162:163] op_sel_hi:[1,0]
	v_bfe_u32 v108, v186, 16, 1
	v_bfe_u32 v109, v204, 16, 1
	v_bfe_u32 v110, v180, 16, 1
	v_pk_add_f32 v[160:161], v[210:211], v[160:161]
	v_pk_mul_f32 v[166:167], v[114:115], v[162:163] op_sel_hi:[1,0]
	v_pk_mul_f32 v[164:165], v[112:113], v[162:163] op_sel_hi:[1,0]
	v_pk_mul_f32 v[114:115], v[102:103], v[162:163] op_sel_hi:[1,0]
	v_pk_mul_f32 v[112:113], v[100:101], v[162:163] op_sel_hi:[1,0]
	v_pk_mul_f32 v[102:103], v[98:99], v[162:163] op_sel_hi:[1,0]
	v_pk_mul_f32 v[100:101], v[96:97], v[162:163] op_sel_hi:[1,0]
	v_pk_mul_f32 v[98:99], v[90:91], v[162:163] op_sel_hi:[1,0]
	v_pk_mul_f32 v[96:97], v[88:89], v[162:163] op_sel_hi:[1,0]
	v_pk_mul_f32 v[90:91], v[106:107], v[162:163] op_sel_hi:[1,0]
	v_pk_mul_f32 v[88:89], v[104:105], v[162:163] op_sel_hi:[1,0]
	v_bfe_u32 v104, v212, 16, 1
	v_bfe_u32 v105, v198, 16, 1
	v_bfe_u32 v107, v188, 16, 1
	v_bfe_u32 v111, v192, 16, 1
	v_add3_u32 v109, v204, v109, s16
	v_add3_u32 v108, v186, v108, s16
	v_add3_u32 v110, v180, v110, s16
	v_pk_fma_f32 v[178:179], v[178:179], v[162:163], v[160:161]
	v_add3_u32 v105, v198, v105, s16
	v_add3_u32 v104, v212, v104, s16
	v_add3_u32 v107, v188, v107, s16
	v_add3_u32 v111, v192, v111, s16
	v_lshrrev_b32_e32 v108, 16, v108
	v_lshrrev_b32_e32 v109, 16, v109
	v_lshrrev_b32_e32 v160, 16, v110
	v_lshrrev_b32_e32 v110, 16, v111
	v_and_or_b32 v111, v104, s15, v109
	v_and_or_b32 v109, v105, s15, v108
	v_and_or_b32 v108, v107, s15, v160
	v_bfe_u32 v107, v196, 16, 1
	v_add3_u32 v160, v196, v107, s16
	v_bfe_u32 v107, v190, 16, 1
	v_bfe_u32 v105, v202, 16, 1
	v_add3_u32 v107, v190, v107, s16
	v_add3_u32 v105, v202, v105, s16
	v_lshrrev_b32_e32 v172, 16, v107
	v_add_u32_e32 v184, 0x6000, v233
	v_and_or_b32 v105, v105, s15, v172
	ds_read2_b64 v[172:175], v184 offset1:4
	v_bfe_u32 v106, v206, 16, 1
	v_pk_mul_f32 v[94:95], v[94:95], v[162:163] op_sel_hi:[1,0]
	v_pk_mul_f32 v[92:93], v[92:93], v[162:163] op_sel_hi:[1,0]
	v_add3_u32 v106, v206, v106, s16
	v_bfe_u32 v161, v200, 16, 1
	v_bfe_u32 v162, v182, 16, 1
	v_bfe_u32 v163, v194, 16, 1
	v_and_or_b32 v110, v106, s15, v110
	v_bfe_u32 v104, v210, 16, 1
	v_bfe_u32 v106, v208, 16, 1
	v_add3_u32 v161, v200, v161, s16
	v_add3_u32 v163, v194, v163, s16
	v_add3_u32 v162, v182, v162, s16
	v_add3_u32 v104, v210, v104, s16
	v_add3_u32 v106, v208, v106, s16
	v_lshrrev_b32_e32 v107, 16, v161
	v_lshrrev_b32_e32 v161, 16, v162
	v_lshrrev_b32_e32 v162, 16, v163
	v_and_or_b32 v107, v104, s15, v107
	v_and_or_b32 v106, v106, s15, v162
	v_and_or_b32 v104, v160, s15, v161
	s_waitcnt lgkmcnt(0)
; #define MFMA16(a, b, c) __builtin_amdgcn_mfma_f32_16x16x32_bf16((a), (b), (c), 0, 0, 0)
; template <int DQK>
; DI void attn_phase(const bf16_t* Q, int ldq, const bf16_t* K1, int ldk1, const bf16_t* K2, int ldk2, const bf16_t* VT, int ldvt,
;                    bf16_t* O, int ldo, int nheads, int nq, int nkeys, bool causal, float scale, char* smem, int bid, int nb) {
;     ...
; #pragma unroll
;       for (int s = 0; s < 2; ++s)
; #pragma unroll
;         for (int dj = 0; dj < 8; ++dj) {
;           const char* vp = Vs + ((dj * 16 + fr) * LDT + 32 * s + fq * 4) * 2;
;           const s16x4 lo = *(const s16x4*)vp, hi = *(const s16x4*)(vp + 32);
;           const bf16x8 vf = __builtin_shufflevector(lo, hi, 0, 1, 2, 3, 4, 5, 6, 7);
; #pragma unroll
;           for (int mi = 0; mi < 2; ++mi) ot[mi][dj] = MFMA16(vf, pf[mi][s], ot[mi][dj]);
;         }
	v_mfma_f32_16x16x32_bf16 v[160:163], v[172:175], v[128:131], v[156:159]
	v_mfma_f32_16x16x32_bf16 v[156:159], v[172:175], v[108:111], v[168:171]
	ds_read2_b64 v[172:175], v245 offset0:64 offset1:68
	s_nop 1
	ds_read2_b64 v[168:171], v244 offset0:32 offset1:36
	s_waitcnt lgkmcnt(0)
	v_mfma_f32_16x16x32_bf16 v[152:155], v[168:171], v[128:131], v[152:155]
	v_mfma_f32_16x16x32_bf16 v[164:167], v[168:171], v[108:111], v[164:167]
	v_mfma_f32_16x16x32_bf16 v[168:171], v[172:175], v[128:131], v[148:151]
	v_mfma_f32_16x16x32_bf16 v[172:175], v[172:175], v[108:111], v[116:119]
	s_nop 2
	ds_read2_b64 v[116:119], v221 offset0:96 offset1:100
	s_waitcnt lgkmcnt(0)
	v_mfma_f32_16x16x32_bf16 v[186:189], v[116:119], v[108:111], v[112:115]
	s_nop 2
	ds_read2_b64 v[112:115], v215 offset0:128 offset1:132
	s_waitcnt lgkmcnt(0)
	v_mfma_f32_16x16x32_bf16 v[194:197], v[112:115], v[108:111], v[100:103]
	s_nop 2
	ds_read2_b64 v[100:103], v216 offset0:160 offset1:164
	s_waitcnt lgkmcnt(0)
	v_mfma_f32_16x16x32_bf16 v[202:205], v[100:103], v[108:111], v[96:99]
	s_nop 2
	ds_read2_b64 v[96:99], v224 offset0:192 offset1:196
	s_waitcnt lgkmcnt(0)
	v_mfma_f32_16x16x32_bf16 v[206:209], v[96:99], v[128:131], v[124:127]
	v_mfma_f32_16x16x32_bf16 v[92:95], v[96:99], v[108:111], v[92:95]
	ds_read2_b64 v[96:99], v225 offset0:224 offset1:228
	s_waitcnt lgkmcnt(0)
	v_mfma_f32_16x16x32_bf16 v[240:243], v[96:99], v[108:111], v[88:91]
	s_nop 2
	ds_read2_b64 v[88:91], v184 offset0:8 offset1:12
	v_mfma_f32_16x16x32_bf16 v[180:183], v[116:119], v[128:131], v[144:147]
	s_waitcnt lgkmcnt(0)
	v_mfma_f32_16x16x32_bf16 v[148:151], v[88:91], v[132:135], v[160:163]
	v_mfma_f32_16x16x32_bf16 v[116:119], v[88:91], v[104:107], v[156:159]
	ds_read2_b64 v[88:91], v244 offset0:40 offset1:44
	v_mfma_f32_16x16x32_bf16 v[190:193], v[112:115], v[128:131], v[140:143]
	s_waitcnt lgkmcnt(0)
	v_mfma_f32_16x16x32_bf16 v[144:147], v[88:91], v[132:135], v[152:155]
	s_nop 2
	ds_read2_b64 v[152:155], v224 offset0:200 offset1:204
	v_mfma_f32_16x16x32_bf16 v[112:115], v[88:91], v[104:107], v[164:167]
	ds_read2_b64 v[88:91], v245 offset0:72 offset1:76
	s_waitcnt lgkmcnt(0)
	v_mfma_f32_16x16x32_bf16 v[140:143], v[88:91], v[132:135], v[168:171]
	v_mfma_f32_16x16x32_bf16 v[108:111], v[88:91], v[104:107], v[172:175]
	ds_read2_b64 v[88:91], v221 offset0:104 offset1:108
	v_mfma_f32_16x16x32_bf16 v[198:201], v[100:103], v[128:131], v[136:139]
	s_waitcnt lgkmcnt(0)
	v_mfma_f32_16x16x32_bf16 v[136:139], v[88:91], v[132:135], v[180:183]
	s_nop 2
	v_mov_b32_e32 v180, v239
	v_mfma_f32_16x16x32_bf16 v[100:103], v[88:91], v[104:107], v[186:189]
	ds_read2_b64 v[88:91], v215 offset0:136 offset1:140
	v_mfma_f32_16x16x32_bf16 v[210:213], v[96:99], v[128:131], v[120:123]
	s_waitcnt lgkmcnt(0)
	v_mfma_f32_16x16x32_bf16 v[128:131], v[88:91], v[132:135], v[190:193]
	v_mfma_f32_16x16x32_bf16 v[96:99], v[88:91], v[104:107], v[194:197]
	ds_read2_b64 v[88:91], v216 offset0:168 offset1:172
	v_mfma_f32_16x16x32_bf16 v[120:123], v[152:155], v[132:135], v[206:209]
	v_mfma_f32_16x16x32_bf16 v[92:95], v[152:155], v[104:107], v[92:95]
	ds_read2_b64 v[152:155], v225 offset0:232 offset1:236
	s_waitcnt lgkmcnt(1)
	v_mfma_f32_16x16x32_bf16 v[124:127], v[88:91], v[132:135], v[198:201]
	v_mfma_f32_16x16x32_bf16 v[88:91], v[88:91], v[104:107], v[202:205]
	s_waitcnt lgkmcnt(0)
	v_mfma_f32_16x16x32_bf16 v[132:135], v[152:155], v[132:135], v[210:213]
	v_mfma_f32_16x16x32_bf16 v[104:107], v[152:155], v[104:107], v[240:243]
	v_mov_b32_e32 v152, v238
	s_branch .LBB0_1539
